# HGRN2 pass-2 start-state prefix (Sacc = DL*Sacc + SL over preceding superchunks): loads for the next two superchunks kept in flight with counted waits instead of a full drain per 16 loads
# speedup vs baseline: 1.0562x; 1.0009x over previous
; __device__ __forceinline__ void hg2_unit(KP p, int u, unsigned char* shm, int tid) {
;   const int hd = u >> 4, sc = u & 15, h = hd >> 1, d = hd & 1;
;   const HgSrc s = hg_src(p, h, d, false);
;   const int lane = tid & 63, wv = tid >> 6, fr = lane & 15, fq = lane >> 4;
;   const float lbk = ((const float*)(p->ws + WS_LBS))[h * 128 + (tid & 127)];
;   f32x4 Sacc[8];
;   {
;     const float* S0 = (const float*)(p->ws + WS_S0) + (size_t)hd * 16384;
; #pragma unroll
;     for (int nt = 0; nt < 8; ++nt)
; #pragma unroll
;       for (int j = 0; j < 4; ++j) Sacc[nt][j] = S0[(16 * wv + fq * 4 + j) * 128 + nt * 16 + fr];
; #pragma unroll 4
;     for (int q = 0; q < sc; ++q) {
;       const float* SL = (const float*)(p->ws + WS_SLOC) + (size_t)(hd * 16 + q) * 16384; const float* DL = (const float*)(p->ws + WS_DLOC) + (hd * 16 + q) * 128;
; #pragma unroll
;       for (int j = 0; j < 4; ++j) { const float dc = DL[16 * wv + fq * 4 + j];
; #pragma unroll
;         for (int nt = 0; nt < 8; ++nt) Sacc[nt][j] = dc * Sacc[nt][j] + SL[(16 * wv + fq * 4 + j) * 128 + nt * 16 + fr]; }
;     }
.LBB0_72:
	s_ashr_i32 s38, s66, 4
	s_lshl_b32 s33, s66, 2
	s_and_b32 s36, s33, 0xffffff80
	s_ashr_i32 s39, s38, 31
	s_and_b32 s37, s65, 15
	v_or_b32_e32 v0, s36, v38
	s_lshl_b64 s[40:41], s[38:39], 16
	v_ashrrev_i32_e32 v1, 31, v0
	s_add_u32 s40, s52, s40
	v_lshl_add_u64 v[0:1], v[0:1], 2, s[34:35]
	s_addc_u32 s41, s53, s41
	global_load_dword v111, v[0:1], off
	v_lshl_add_u64 v[0:1], v[40:41], 2, s[40:41]
	v_lshl_add_u64 v[28:29], v[44:45], 2, s[40:41]
	v_lshl_add_u64 v[2:3], v[42:43], 2, s[40:41]
	v_lshl_add_u64 v[8:9], v[46:47], 2, s[40:41]
	v_lshl_add_u64 v[30:31], v[48:49], 2, s[40:41]
	v_lshl_add_u64 v[12:13], v[50:51], 2, s[40:41]
	v_lshl_add_u64 v[16:17], v[52:53], 2, s[40:41]
	v_lshl_add_u64 v[20:21], v[54:55], 2, s[40:41]
	v_lshl_add_u64 v[24:25], v[56:57], 2, s[40:41]
	v_lshl_add_u64 v[32:33], v[58:59], 2, s[40:41]
	global_load_dword v0, v[0:1], off
	s_and_b32 s46, s66, 15
	global_load_dword v1, v[28:29], off offset:512
	s_nop 0
	global_load_dword v2, v[2:3], off
	s_nop 0
	global_load_dword v3, v[28:29], off offset:1536
	global_load_dword v4, v[28:29], off offset:64
	global_load_dword v5, v[8:9], off offset:512
	global_load_dword v6, v[30:31], off offset:64
	global_load_dword v7, v[8:9], off offset:1536
	s_nop 0
	global_load_dword v8, v[28:29], off offset:128
	global_load_dword v9, v[12:13], off offset:512
	global_load_dword v10, v[30:31], off offset:128
	global_load_dword v11, v[12:13], off offset:1536
	s_nop 0
	global_load_dword v12, v[28:29], off offset:192
	global_load_dword v13, v[16:17], off offset:512
	global_load_dword v14, v[30:31], off offset:192
	global_load_dword v15, v[16:17], off offset:1536
	s_nop 0
	global_load_dword v16, v[28:29], off offset:256
	global_load_dword v17, v[20:21], off offset:512
	global_load_dword v18, v[30:31], off offset:256
	global_load_dword v19, v[20:21], off offset:1536
	s_nop 0
	global_load_dword v20, v[28:29], off offset:320
	global_load_dword v21, v[24:25], off offset:512
	global_load_dword v22, v[30:31], off offset:320
	global_load_dword v23, v[24:25], off offset:1536
	s_nop 0
	global_load_dword v24, v[28:29], off offset:384
	global_load_dword v25, v[32:33], off offset:512
	global_load_dword v26, v[30:31], off offset:384
	global_load_dword v27, v[32:33], off offset:1536
	s_nop 0
	global_load_dword v28, v[28:29], off offset:448
	v_lshl_add_u64 v[32:33], v[60:61], 2, s[40:41]
	global_load_dword v29, v[32:33], off offset:512
	s_nop 0
	global_load_dword v30, v[30:31], off offset:448
	s_nop 0
	global_load_dword v31, v[32:33], off offset:1536
	s_cmp_eq_u32 s46, 0
	s_cbranch_scc1 .LBB0_79
	s_and_b32 s39, s66, -16
	s_lshl_b32 s33, s66, 7
	s_and_b32 s33, s33, 0xfffff800
	s_add_i32 s47, s46, -1
	s_mov_b32 s48, 0
	s_add_i32 s42, s39, s48
	s_ashr_i32 s43, s42, 31
	s_lshl_b64 s[44:45], s[42:43], 16
	s_add_u32 s44, s55, s44
	s_addc_u32 s45, s56, s45
	v_lshl_add_u64 v[132:133], v[40:41], 2, s[44:45]
	s_lshl_b32 s40, s48, 7
	s_add_i32 s40, s40, s33
	s_ashr_i32 s41, s40, 31
	v_lshl_add_u64 v[32:33], s[40:41], 2, v[62:63]
	global_load_dwordx4 v[212:215], v[32:33], off
	global_load_dword v148, v[132:133], off
	global_load_dword v149, v[132:133], off offset:512
	global_load_dword v150, v[132:133], off offset:1024
	global_load_dword v151, v[132:133], off offset:1536
	global_load_dword v152, v[132:133], off offset:64
	global_load_dword v153, v[132:133], off offset:576
	global_load_dword v154, v[132:133], off offset:1088
	global_load_dword v155, v[132:133], off offset:1600
	global_load_dword v156, v[132:133], off offset:128
	global_load_dword v157, v[132:133], off offset:640
	global_load_dword v158, v[132:133], off offset:1152
	global_load_dword v159, v[132:133], off offset:1664
	global_load_dword v160, v[132:133], off offset:192
	global_load_dword v161, v[132:133], off offset:704
	global_load_dword v162, v[132:133], off offset:1216
	global_load_dword v163, v[132:133], off offset:1728
	global_load_dword v164, v[132:133], off offset:256
	global_load_dword v165, v[132:133], off offset:768
	global_load_dword v166, v[132:133], off offset:1280
	global_load_dword v167, v[132:133], off offset:1792
	global_load_dword v168, v[132:133], off offset:320
	global_load_dword v169, v[132:133], off offset:832
	global_load_dword v170, v[132:133], off offset:1344
	global_load_dword v171, v[132:133], off offset:1856
	global_load_dword v172, v[132:133], off offset:384
	global_load_dword v173, v[132:133], off offset:896
	global_load_dword v174, v[132:133], off offset:1408
	global_load_dword v175, v[132:133], off offset:1920
	global_load_dword v176, v[132:133], off offset:448
	global_load_dword v177, v[132:133], off offset:960
	global_load_dword v178, v[132:133], off offset:1472
	global_load_dword v179, v[132:133], off offset:1984
	s_min_i32 s48, 1, s47
	s_add_i32 s42, s39, s48
	s_ashr_i32 s43, s42, 31
	s_lshl_b64 s[44:45], s[42:43], 16
	s_add_u32 s44, s55, s44
	s_addc_u32 s45, s56, s45
	v_lshl_add_u64 v[134:135], v[40:41], 2, s[44:45]
	s_lshl_b32 s40, s48, 7
	s_add_i32 s40, s40, s33
	s_ashr_i32 s41, s40, 31
	v_lshl_add_u64 v[32:33], s[40:41], 2, v[62:63]
	global_load_dwordx4 v[216:219], v[32:33], off
	global_load_dword v180, v[134:135], off
	global_load_dword v181, v[134:135], off offset:512
	global_load_dword v182, v[134:135], off offset:1024
	global_load_dword v183, v[134:135], off offset:1536
	global_load_dword v184, v[134:135], off offset:64
	global_load_dword v185, v[134:135], off offset:576
	global_load_dword v186, v[134:135], off offset:1088
	global_load_dword v187, v[134:135], off offset:1600
	global_load_dword v188, v[134:135], off offset:128
	global_load_dword v189, v[134:135], off offset:640
	global_load_dword v190, v[134:135], off offset:1152
	global_load_dword v191, v[134:135], off offset:1664
	global_load_dword v192, v[134:135], off offset:192
	global_load_dword v193, v[134:135], off offset:704
	global_load_dword v194, v[134:135], off offset:1216
	global_load_dword v195, v[134:135], off offset:1728
	global_load_dword v196, v[134:135], off offset:256
	global_load_dword v197, v[134:135], off offset:768
	global_load_dword v198, v[134:135], off offset:1280
	global_load_dword v199, v[134:135], off offset:1792
	global_load_dword v200, v[134:135], off offset:320
	global_load_dword v201, v[134:135], off offset:832
	global_load_dword v202, v[134:135], off offset:1344
	global_load_dword v203, v[134:135], off offset:1856
	global_load_dword v204, v[134:135], off offset:384
	global_load_dword v205, v[134:135], off offset:896
	global_load_dword v206, v[134:135], off offset:1408
	global_load_dword v207, v[134:135], off offset:1920
	global_load_dword v208, v[134:135], off offset:448
	global_load_dword v209, v[134:135], off offset:960
	global_load_dword v210, v[134:135], off offset:1472
	global_load_dword v211, v[134:135], off offset:1984
	s_waitcnt vmcnt(33)
; __device__ __forceinline__ void hg2_unit(KP p, int u, unsigned char* shm, int tid) {
;     ...
;     for (int q = 0; q < sc; ++q) {
;       const float* SL = (const float*)(p->ws + WS_SLOC) + (size_t)(hd * 16 + q) * 16384; const float* DL = (const float*)(p->ws + WS_DLOC) + (hd * 16 + q) * 128;
; #pragma unroll
;       for (int j = 0; j < 4; ++j) { const float dc = DL[16 * wv + fq * 4 + j];
; #pragma unroll
;         for (int nt = 0; nt < 8; ++nt) Sacc[nt][j] = dc * Sacc[nt][j] + SL[(16 * wv + fq * 4 + j) * 128 + nt * 16 + fr]; }
;     }
	s_min_i32 s48, 2, s47
	s_add_i32 s42, s39, s48
	s_ashr_i32 s43, s42, 31
	s_lshl_b64 s[44:45], s[42:43], 16
	s_add_u32 s44, s55, s44
	s_addc_u32 s45, s56, s45
	v_lshl_add_u64 v[136:137], v[40:41], 2, s[44:45]
	s_lshl_b32 s40, s48, 7
	s_add_i32 s40, s40, s33
	s_ashr_i32 s41, s40, 31
	v_lshl_add_u64 v[32:33], s[40:41], 2, v[62:63]
	global_load_dwordx4 v[128:131], v[32:33], off
	global_load_dword v68, v[136:137], off
	global_load_dword v69, v[136:137], off offset:512
	global_load_dword v70, v[136:137], off offset:1024
	global_load_dword v71, v[136:137], off offset:1536
	global_load_dword v72, v[136:137], off offset:64
	global_load_dword v73, v[136:137], off offset:576
	global_load_dword v74, v[136:137], off offset:1088
	global_load_dword v75, v[136:137], off offset:1600
	global_load_dword v76, v[136:137], off offset:128
	global_load_dword v77, v[136:137], off offset:640
	global_load_dword v78, v[136:137], off offset:1152
	global_load_dword v79, v[136:137], off offset:1664
	global_load_dword v80, v[136:137], off offset:192
	global_load_dword v81, v[136:137], off offset:704
	global_load_dword v82, v[136:137], off offset:1216
	global_load_dword v83, v[136:137], off offset:1728
	global_load_dword v112, v[136:137], off offset:256
	global_load_dword v113, v[136:137], off offset:768
	global_load_dword v114, v[136:137], off offset:1280
	global_load_dword v115, v[136:137], off offset:1792
	global_load_dword v116, v[136:137], off offset:320
	global_load_dword v117, v[136:137], off offset:832
	global_load_dword v118, v[136:137], off offset:1344
	global_load_dword v119, v[136:137], off offset:1856
	global_load_dword v120, v[136:137], off offset:384
	global_load_dword v121, v[136:137], off offset:896
	global_load_dword v122, v[136:137], off offset:1408
	global_load_dword v123, v[136:137], off offset:1920
	global_load_dword v124, v[136:137], off offset:448
	global_load_dword v125, v[136:137], off offset:960
	global_load_dword v126, v[136:137], off offset:1472
	global_load_dword v127, v[136:137], off offset:1984
	v_pk_fma_f32 v[0:1], v[0:1], v[212:213], v[148:149]
	v_pk_fma_f32 v[2:3], v[2:3], v[214:215], v[150:151]
	v_pk_fma_f32 v[4:5], v[4:5], v[212:213], v[152:153]
	v_pk_fma_f32 v[6:7], v[6:7], v[214:215], v[154:155]
	v_pk_fma_f32 v[8:9], v[8:9], v[212:213], v[156:157]
	v_pk_fma_f32 v[10:11], v[10:11], v[214:215], v[158:159]
	v_pk_fma_f32 v[12:13], v[12:13], v[212:213], v[160:161]
	v_pk_fma_f32 v[14:15], v[14:15], v[214:215], v[162:163]
	v_pk_fma_f32 v[16:17], v[16:17], v[212:213], v[164:165]
	v_pk_fma_f32 v[18:19], v[18:19], v[214:215], v[166:167]
	v_pk_fma_f32 v[20:21], v[20:21], v[212:213], v[168:169]
	v_pk_fma_f32 v[22:23], v[22:23], v[214:215], v[170:171]
	v_pk_fma_f32 v[24:25], v[24:25], v[212:213], v[172:173]
	v_pk_fma_f32 v[26:27], v[26:27], v[214:215], v[174:175]
	v_pk_fma_f32 v[28:29], v[28:29], v[212:213], v[176:177]
	v_pk_fma_f32 v[30:31], v[30:31], v[214:215], v[178:179]
	s_cmp_eq_u32 s46, 1
	s_cbranch_scc1 .Lpf_done
	s_waitcnt vmcnt(33)
	s_min_i32 s48, 3, s47
	s_add_i32 s42, s39, s48
	s_ashr_i32 s43, s42, 31
	s_lshl_b64 s[44:45], s[42:43], 16
	s_add_u32 s44, s55, s44
	s_addc_u32 s45, s56, s45
	v_lshl_add_u64 v[132:133], v[40:41], 2, s[44:45]
	s_lshl_b32 s40, s48, 7
	s_add_i32 s40, s40, s33
	s_ashr_i32 s41, s40, 31
	v_lshl_add_u64 v[32:33], s[40:41], 2, v[62:63]
	global_load_dwordx4 v[212:215], v[32:33], off
	global_load_dword v148, v[132:133], off
	global_load_dword v149, v[132:133], off offset:512
	global_load_dword v150, v[132:133], off offset:1024
	global_load_dword v151, v[132:133], off offset:1536
	global_load_dword v152, v[132:133], off offset:64
	global_load_dword v153, v[132:133], off offset:576
	global_load_dword v154, v[132:133], off offset:1088
	global_load_dword v155, v[132:133], off offset:1600
	global_load_dword v156, v[132:133], off offset:128
	global_load_dword v157, v[132:133], off offset:640
	global_load_dword v158, v[132:133], off offset:1152
	global_load_dword v159, v[132:133], off offset:1664
	global_load_dword v160, v[132:133], off offset:192
	global_load_dword v161, v[132:133], off offset:704
	global_load_dword v162, v[132:133], off offset:1216
	global_load_dword v163, v[132:133], off offset:1728
	global_load_dword v164, v[132:133], off offset:256
	global_load_dword v165, v[132:133], off offset:768
	global_load_dword v166, v[132:133], off offset:1280
	global_load_dword v167, v[132:133], off offset:1792
	global_load_dword v168, v[132:133], off offset:320
	global_load_dword v169, v[132:133], off offset:832
	global_load_dword v170, v[132:133], off offset:1344
	global_load_dword v171, v[132:133], off offset:1856
	global_load_dword v172, v[132:133], off offset:384
	global_load_dword v173, v[132:133], off offset:896
	global_load_dword v174, v[132:133], off offset:1408
	global_load_dword v175, v[132:133], off offset:1920
	global_load_dword v176, v[132:133], off offset:448
	global_load_dword v177, v[132:133], off offset:960
	global_load_dword v178, v[132:133], off offset:1472
	global_load_dword v179, v[132:133], off offset:1984
	v_pk_fma_f32 v[0:1], v[0:1], v[216:217], v[180:181]
	v_pk_fma_f32 v[2:3], v[2:3], v[218:219], v[182:183]
	v_pk_fma_f32 v[4:5], v[4:5], v[216:217], v[184:185]
	v_pk_fma_f32 v[6:7], v[6:7], v[218:219], v[186:187]
	v_pk_fma_f32 v[8:9], v[8:9], v[216:217], v[188:189]
	v_pk_fma_f32 v[10:11], v[10:11], v[218:219], v[190:191]
	v_pk_fma_f32 v[12:13], v[12:13], v[216:217], v[192:193]
	v_pk_fma_f32 v[14:15], v[14:15], v[218:219], v[194:195]
	v_pk_fma_f32 v[16:17], v[16:17], v[216:217], v[196:197]
	v_pk_fma_f32 v[18:19], v[18:19], v[218:219], v[198:199]
	v_pk_fma_f32 v[20:21], v[20:21], v[216:217], v[200:201]
	v_pk_fma_f32 v[22:23], v[22:23], v[218:219], v[202:203]
	v_pk_fma_f32 v[24:25], v[24:25], v[216:217], v[204:205]
	v_pk_fma_f32 v[26:27], v[26:27], v[218:219], v[206:207]
	v_pk_fma_f32 v[28:29], v[28:29], v[216:217], v[208:209]
	v_pk_fma_f32 v[30:31], v[30:31], v[218:219], v[210:211]
	s_cmp_eq_u32 s46, 2
	s_cbranch_scc1 .Lpf_done
; __device__ __forceinline__ void hg2_unit(KP p, int u, unsigned char* shm, int tid) {
;     ...
;     for (int q = 0; q < sc; ++q) {
;       const float* SL = (const float*)(p->ws + WS_SLOC) + (size_t)(hd * 16 + q) * 16384; const float* DL = (const float*)(p->ws + WS_DLOC) + (hd * 16 + q) * 128;
; #pragma unroll
;       for (int j = 0; j < 4; ++j) { const float dc = DL[16 * wv + fq * 4 + j];
; #pragma unroll
;         for (int nt = 0; nt < 8; ++nt) Sacc[nt][j] = dc * Sacc[nt][j] + SL[(16 * wv + fq * 4 + j) * 128 + nt * 16 + fr]; }
;     }
	s_waitcnt vmcnt(33)
	s_min_i32 s48, 4, s47
	s_add_i32 s42, s39, s48
	s_ashr_i32 s43, s42, 31
	s_lshl_b64 s[44:45], s[42:43], 16
	s_add_u32 s44, s55, s44
	s_addc_u32 s45, s56, s45
	v_lshl_add_u64 v[134:135], v[40:41], 2, s[44:45]
	s_lshl_b32 s40, s48, 7
	s_add_i32 s40, s40, s33
	s_ashr_i32 s41, s40, 31
	v_lshl_add_u64 v[32:33], s[40:41], 2, v[62:63]
	global_load_dwordx4 v[216:219], v[32:33], off
	global_load_dword v180, v[134:135], off
	global_load_dword v181, v[134:135], off offset:512
	global_load_dword v182, v[134:135], off offset:1024
	global_load_dword v183, v[134:135], off offset:1536
	global_load_dword v184, v[134:135], off offset:64
	global_load_dword v185, v[134:135], off offset:576
	global_load_dword v186, v[134:135], off offset:1088
	global_load_dword v187, v[134:135], off offset:1600
	global_load_dword v188, v[134:135], off offset:128
	global_load_dword v189, v[134:135], off offset:640
	global_load_dword v190, v[134:135], off offset:1152
	global_load_dword v191, v[134:135], off offset:1664
	global_load_dword v192, v[134:135], off offset:192
	global_load_dword v193, v[134:135], off offset:704
	global_load_dword v194, v[134:135], off offset:1216
	global_load_dword v195, v[134:135], off offset:1728
	global_load_dword v196, v[134:135], off offset:256
	global_load_dword v197, v[134:135], off offset:768
	global_load_dword v198, v[134:135], off offset:1280
	global_load_dword v199, v[134:135], off offset:1792
	global_load_dword v200, v[134:135], off offset:320
	global_load_dword v201, v[134:135], off offset:832
	global_load_dword v202, v[134:135], off offset:1344
	global_load_dword v203, v[134:135], off offset:1856
	global_load_dword v204, v[134:135], off offset:384
	global_load_dword v205, v[134:135], off offset:896
	global_load_dword v206, v[134:135], off offset:1408
	global_load_dword v207, v[134:135], off offset:1920
	global_load_dword v208, v[134:135], off offset:448
	global_load_dword v209, v[134:135], off offset:960
	global_load_dword v210, v[134:135], off offset:1472
	global_load_dword v211, v[134:135], off offset:1984
	v_pk_fma_f32 v[0:1], v[0:1], v[128:129], v[68:69]
	v_pk_fma_f32 v[2:3], v[2:3], v[130:131], v[70:71]
	v_pk_fma_f32 v[4:5], v[4:5], v[128:129], v[72:73]
	v_pk_fma_f32 v[6:7], v[6:7], v[130:131], v[74:75]
	v_pk_fma_f32 v[8:9], v[8:9], v[128:129], v[76:77]
	v_pk_fma_f32 v[10:11], v[10:11], v[130:131], v[78:79]
	v_pk_fma_f32 v[12:13], v[12:13], v[128:129], v[80:81]
	v_pk_fma_f32 v[14:15], v[14:15], v[130:131], v[82:83]
	v_pk_fma_f32 v[16:17], v[16:17], v[128:129], v[112:113]
	v_pk_fma_f32 v[18:19], v[18:19], v[130:131], v[114:115]
	v_pk_fma_f32 v[20:21], v[20:21], v[128:129], v[116:117]
	v_pk_fma_f32 v[22:23], v[22:23], v[130:131], v[118:119]
	v_pk_fma_f32 v[24:25], v[24:25], v[128:129], v[120:121]
	v_pk_fma_f32 v[26:27], v[26:27], v[130:131], v[122:123]
	v_pk_fma_f32 v[28:29], v[28:29], v[128:129], v[124:125]
	v_pk_fma_f32 v[30:31], v[30:31], v[130:131], v[126:127]
	s_cmp_eq_u32 s46, 3
	s_cbranch_scc1 .Lpf_done
	s_waitcnt vmcnt(33)
	s_min_i32 s48, 5, s47
	s_add_i32 s42, s39, s48
	s_ashr_i32 s43, s42, 31
	s_lshl_b64 s[44:45], s[42:43], 16
	s_add_u32 s44, s55, s44
	s_addc_u32 s45, s56, s45
	v_lshl_add_u64 v[136:137], v[40:41], 2, s[44:45]
	s_lshl_b32 s40, s48, 7
	s_add_i32 s40, s40, s33
	s_ashr_i32 s41, s40, 31
	v_lshl_add_u64 v[32:33], s[40:41], 2, v[62:63]
	global_load_dwordx4 v[128:131], v[32:33], off
	global_load_dword v68, v[136:137], off
	global_load_dword v69, v[136:137], off offset:512
	global_load_dword v70, v[136:137], off offset:1024
	global_load_dword v71, v[136:137], off offset:1536
	global_load_dword v72, v[136:137], off offset:64
	global_load_dword v73, v[136:137], off offset:576
	global_load_dword v74, v[136:137], off offset:1088
	global_load_dword v75, v[136:137], off offset:1600
	global_load_dword v76, v[136:137], off offset:128
	global_load_dword v77, v[136:137], off offset:640
	global_load_dword v78, v[136:137], off offset:1152
	global_load_dword v79, v[136:137], off offset:1664
	global_load_dword v80, v[136:137], off offset:192
	global_load_dword v81, v[136:137], off offset:704
	global_load_dword v82, v[136:137], off offset:1216
	global_load_dword v83, v[136:137], off offset:1728
	global_load_dword v112, v[136:137], off offset:256
	global_load_dword v113, v[136:137], off offset:768
	global_load_dword v114, v[136:137], off offset:1280
	global_load_dword v115, v[136:137], off offset:1792
	global_load_dword v116, v[136:137], off offset:320
	global_load_dword v117, v[136:137], off offset:832
	global_load_dword v118, v[136:137], off offset:1344
	global_load_dword v119, v[136:137], off offset:1856
	global_load_dword v120, v[136:137], off offset:384
	global_load_dword v121, v[136:137], off offset:896
	global_load_dword v122, v[136:137], off offset:1408
	global_load_dword v123, v[136:137], off offset:1920
	global_load_dword v124, v[136:137], off offset:448
	global_load_dword v125, v[136:137], off offset:960
	global_load_dword v126, v[136:137], off offset:1472
	global_load_dword v127, v[136:137], off offset:1984
	v_pk_fma_f32 v[0:1], v[0:1], v[212:213], v[148:149]
	v_pk_fma_f32 v[2:3], v[2:3], v[214:215], v[150:151]
	v_pk_fma_f32 v[4:5], v[4:5], v[212:213], v[152:153]
	v_pk_fma_f32 v[6:7], v[6:7], v[214:215], v[154:155]
	v_pk_fma_f32 v[8:9], v[8:9], v[212:213], v[156:157]
	v_pk_fma_f32 v[10:11], v[10:11], v[214:215], v[158:159]
	v_pk_fma_f32 v[12:13], v[12:13], v[212:213], v[160:161]
	v_pk_fma_f32 v[14:15], v[14:15], v[214:215], v[162:163]
	v_pk_fma_f32 v[16:17], v[16:17], v[212:213], v[164:165]
	v_pk_fma_f32 v[18:19], v[18:19], v[214:215], v[166:167]
	v_pk_fma_f32 v[20:21], v[20:21], v[212:213], v[168:169]
	v_pk_fma_f32 v[22:23], v[22:23], v[214:215], v[170:171]
	v_pk_fma_f32 v[24:25], v[24:25], v[212:213], v[172:173]
	v_pk_fma_f32 v[26:27], v[26:27], v[214:215], v[174:175]
	v_pk_fma_f32 v[28:29], v[28:29], v[212:213], v[176:177]
	v_pk_fma_f32 v[30:31], v[30:31], v[214:215], v[178:179]
	s_cmp_eq_u32 s46, 4
	s_cbranch_scc1 .Lpf_done
; __device__ __forceinline__ void hg2_unit(KP p, int u, unsigned char* shm, int tid) {
;     ...
;     for (int q = 0; q < sc; ++q) {
;       const float* SL = (const float*)(p->ws + WS_SLOC) + (size_t)(hd * 16 + q) * 16384; const float* DL = (const float*)(p->ws + WS_DLOC) + (hd * 16 + q) * 128;
; #pragma unroll
;       for (int j = 0; j < 4; ++j) { const float dc = DL[16 * wv + fq * 4 + j];
; #pragma unroll
;         for (int nt = 0; nt < 8; ++nt) Sacc[nt][j] = dc * Sacc[nt][j] + SL[(16 * wv + fq * 4 + j) * 128 + nt * 16 + fr]; }
;     }
	s_waitcnt vmcnt(33)
	s_min_i32 s48, 6, s47
	s_add_i32 s42, s39, s48
	s_ashr_i32 s43, s42, 31
	s_lshl_b64 s[44:45], s[42:43], 16
	s_add_u32 s44, s55, s44
	s_addc_u32 s45, s56, s45
	v_lshl_add_u64 v[132:133], v[40:41], 2, s[44:45]
	s_lshl_b32 s40, s48, 7
	s_add_i32 s40, s40, s33
	s_ashr_i32 s41, s40, 31
	v_lshl_add_u64 v[32:33], s[40:41], 2, v[62:63]
	global_load_dwordx4 v[212:215], v[32:33], off
	global_load_dword v148, v[132:133], off
	global_load_dword v149, v[132:133], off offset:512
	global_load_dword v150, v[132:133], off offset:1024
	global_load_dword v151, v[132:133], off offset:1536
	global_load_dword v152, v[132:133], off offset:64
	global_load_dword v153, v[132:133], off offset:576
	global_load_dword v154, v[132:133], off offset:1088
	global_load_dword v155, v[132:133], off offset:1600
	global_load_dword v156, v[132:133], off offset:128
	global_load_dword v157, v[132:133], off offset:640
	global_load_dword v158, v[132:133], off offset:1152
	global_load_dword v159, v[132:133], off offset:1664
	global_load_dword v160, v[132:133], off offset:192
	global_load_dword v161, v[132:133], off offset:704
	global_load_dword v162, v[132:133], off offset:1216
	global_load_dword v163, v[132:133], off offset:1728
	global_load_dword v164, v[132:133], off offset:256
	global_load_dword v165, v[132:133], off offset:768
	global_load_dword v166, v[132:133], off offset:1280
	global_load_dword v167, v[132:133], off offset:1792
	global_load_dword v168, v[132:133], off offset:320
	global_load_dword v169, v[132:133], off offset:832
	global_load_dword v170, v[132:133], off offset:1344
	global_load_dword v171, v[132:133], off offset:1856
	global_load_dword v172, v[132:133], off offset:384
	global_load_dword v173, v[132:133], off offset:896
	global_load_dword v174, v[132:133], off offset:1408
	global_load_dword v175, v[132:133], off offset:1920
	global_load_dword v176, v[132:133], off offset:448
	global_load_dword v177, v[132:133], off offset:960
	global_load_dword v178, v[132:133], off offset:1472
	global_load_dword v179, v[132:133], off offset:1984
	v_pk_fma_f32 v[0:1], v[0:1], v[216:217], v[180:181]
	v_pk_fma_f32 v[2:3], v[2:3], v[218:219], v[182:183]
	v_pk_fma_f32 v[4:5], v[4:5], v[216:217], v[184:185]
	v_pk_fma_f32 v[6:7], v[6:7], v[218:219], v[186:187]
	v_pk_fma_f32 v[8:9], v[8:9], v[216:217], v[188:189]
	v_pk_fma_f32 v[10:11], v[10:11], v[218:219], v[190:191]
	v_pk_fma_f32 v[12:13], v[12:13], v[216:217], v[192:193]
	v_pk_fma_f32 v[14:15], v[14:15], v[218:219], v[194:195]
	v_pk_fma_f32 v[16:17], v[16:17], v[216:217], v[196:197]
	v_pk_fma_f32 v[18:19], v[18:19], v[218:219], v[198:199]
	v_pk_fma_f32 v[20:21], v[20:21], v[216:217], v[200:201]
	v_pk_fma_f32 v[22:23], v[22:23], v[218:219], v[202:203]
	v_pk_fma_f32 v[24:25], v[24:25], v[216:217], v[204:205]
	v_pk_fma_f32 v[26:27], v[26:27], v[218:219], v[206:207]
	v_pk_fma_f32 v[28:29], v[28:29], v[216:217], v[208:209]
	v_pk_fma_f32 v[30:31], v[30:31], v[218:219], v[210:211]
	s_cmp_eq_u32 s46, 5
	s_cbranch_scc1 .Lpf_done
	s_waitcnt vmcnt(33)
	s_min_i32 s48, 7, s47
	s_add_i32 s42, s39, s48
	s_ashr_i32 s43, s42, 31
	s_lshl_b64 s[44:45], s[42:43], 16
	s_add_u32 s44, s55, s44
	s_addc_u32 s45, s56, s45
	v_lshl_add_u64 v[134:135], v[40:41], 2, s[44:45]
	s_lshl_b32 s40, s48, 7
	s_add_i32 s40, s40, s33
	s_ashr_i32 s41, s40, 31
	v_lshl_add_u64 v[32:33], s[40:41], 2, v[62:63]
	global_load_dwordx4 v[216:219], v[32:33], off
	global_load_dword v180, v[134:135], off
	global_load_dword v181, v[134:135], off offset:512
	global_load_dword v182, v[134:135], off offset:1024
	global_load_dword v183, v[134:135], off offset:1536
	global_load_dword v184, v[134:135], off offset:64
	global_load_dword v185, v[134:135], off offset:576
	global_load_dword v186, v[134:135], off offset:1088
	global_load_dword v187, v[134:135], off offset:1600
	global_load_dword v188, v[134:135], off offset:128
	global_load_dword v189, v[134:135], off offset:640
	global_load_dword v190, v[134:135], off offset:1152
	global_load_dword v191, v[134:135], off offset:1664
	global_load_dword v192, v[134:135], off offset:192
	global_load_dword v193, v[134:135], off offset:704
	global_load_dword v194, v[134:135], off offset:1216
	global_load_dword v195, v[134:135], off offset:1728
	global_load_dword v196, v[134:135], off offset:256
	global_load_dword v197, v[134:135], off offset:768
	global_load_dword v198, v[134:135], off offset:1280
	global_load_dword v199, v[134:135], off offset:1792
	global_load_dword v200, v[134:135], off offset:320
	global_load_dword v201, v[134:135], off offset:832
	global_load_dword v202, v[134:135], off offset:1344
	global_load_dword v203, v[134:135], off offset:1856
	global_load_dword v204, v[134:135], off offset:384
	global_load_dword v205, v[134:135], off offset:896
	global_load_dword v206, v[134:135], off offset:1408
	global_load_dword v207, v[134:135], off offset:1920
	global_load_dword v208, v[134:135], off offset:448
	global_load_dword v209, v[134:135], off offset:960
	global_load_dword v210, v[134:135], off offset:1472
	global_load_dword v211, v[134:135], off offset:1984
	v_pk_fma_f32 v[0:1], v[0:1], v[128:129], v[68:69]
	v_pk_fma_f32 v[2:3], v[2:3], v[130:131], v[70:71]
	v_pk_fma_f32 v[4:5], v[4:5], v[128:129], v[72:73]
	v_pk_fma_f32 v[6:7], v[6:7], v[130:131], v[74:75]
	v_pk_fma_f32 v[8:9], v[8:9], v[128:129], v[76:77]
	v_pk_fma_f32 v[10:11], v[10:11], v[130:131], v[78:79]
	v_pk_fma_f32 v[12:13], v[12:13], v[128:129], v[80:81]
	v_pk_fma_f32 v[14:15], v[14:15], v[130:131], v[82:83]
	v_pk_fma_f32 v[16:17], v[16:17], v[128:129], v[112:113]
	v_pk_fma_f32 v[18:19], v[18:19], v[130:131], v[114:115]
	v_pk_fma_f32 v[20:21], v[20:21], v[128:129], v[116:117]
	v_pk_fma_f32 v[22:23], v[22:23], v[130:131], v[118:119]
	v_pk_fma_f32 v[24:25], v[24:25], v[128:129], v[120:121]
	v_pk_fma_f32 v[26:27], v[26:27], v[130:131], v[122:123]
	v_pk_fma_f32 v[28:29], v[28:29], v[128:129], v[124:125]
	v_pk_fma_f32 v[30:31], v[30:31], v[130:131], v[126:127]
	s_cmp_eq_u32 s46, 6
	s_cbranch_scc1 .Lpf_done
; __device__ __forceinline__ void hg2_unit(KP p, int u, unsigned char* shm, int tid) {
;     ...
;     for (int q = 0; q < sc; ++q) {
;       const float* SL = (const float*)(p->ws + WS_SLOC) + (size_t)(hd * 16 + q) * 16384; const float* DL = (const float*)(p->ws + WS_DLOC) + (hd * 16 + q) * 128;
; #pragma unroll
;       for (int j = 0; j < 4; ++j) { const float dc = DL[16 * wv + fq * 4 + j];
; #pragma unroll
;         for (int nt = 0; nt < 8; ++nt) Sacc[nt][j] = dc * Sacc[nt][j] + SL[(16 * wv + fq * 4 + j) * 128 + nt * 16 + fr]; }
;     }
	s_waitcnt vmcnt(33)
	s_min_i32 s48, 8, s47
	s_add_i32 s42, s39, s48
	s_ashr_i32 s43, s42, 31
	s_lshl_b64 s[44:45], s[42:43], 16
	s_add_u32 s44, s55, s44
	s_addc_u32 s45, s56, s45
	v_lshl_add_u64 v[136:137], v[40:41], 2, s[44:45]
	s_lshl_b32 s40, s48, 7
	s_add_i32 s40, s40, s33
	s_ashr_i32 s41, s40, 31
	v_lshl_add_u64 v[32:33], s[40:41], 2, v[62:63]
	global_load_dwordx4 v[128:131], v[32:33], off
	global_load_dword v68, v[136:137], off
	global_load_dword v69, v[136:137], off offset:512
	global_load_dword v70, v[136:137], off offset:1024
	global_load_dword v71, v[136:137], off offset:1536
	global_load_dword v72, v[136:137], off offset:64
	global_load_dword v73, v[136:137], off offset:576
	global_load_dword v74, v[136:137], off offset:1088
	global_load_dword v75, v[136:137], off offset:1600
	global_load_dword v76, v[136:137], off offset:128
	global_load_dword v77, v[136:137], off offset:640
	global_load_dword v78, v[136:137], off offset:1152
	global_load_dword v79, v[136:137], off offset:1664
	global_load_dword v80, v[136:137], off offset:192
	global_load_dword v81, v[136:137], off offset:704
	global_load_dword v82, v[136:137], off offset:1216
	global_load_dword v83, v[136:137], off offset:1728
	global_load_dword v112, v[136:137], off offset:256
	global_load_dword v113, v[136:137], off offset:768
	global_load_dword v114, v[136:137], off offset:1280
	global_load_dword v115, v[136:137], off offset:1792
	global_load_dword v116, v[136:137], off offset:320
	global_load_dword v117, v[136:137], off offset:832
	global_load_dword v118, v[136:137], off offset:1344
	global_load_dword v119, v[136:137], off offset:1856
	global_load_dword v120, v[136:137], off offset:384
	global_load_dword v121, v[136:137], off offset:896
	global_load_dword v122, v[136:137], off offset:1408
	global_load_dword v123, v[136:137], off offset:1920
	global_load_dword v124, v[136:137], off offset:448
	global_load_dword v125, v[136:137], off offset:960
	global_load_dword v126, v[136:137], off offset:1472
	global_load_dword v127, v[136:137], off offset:1984
	v_pk_fma_f32 v[0:1], v[0:1], v[212:213], v[148:149]
	v_pk_fma_f32 v[2:3], v[2:3], v[214:215], v[150:151]
	v_pk_fma_f32 v[4:5], v[4:5], v[212:213], v[152:153]
	v_pk_fma_f32 v[6:7], v[6:7], v[214:215], v[154:155]
	v_pk_fma_f32 v[8:9], v[8:9], v[212:213], v[156:157]
	v_pk_fma_f32 v[10:11], v[10:11], v[214:215], v[158:159]
	v_pk_fma_f32 v[12:13], v[12:13], v[212:213], v[160:161]
	v_pk_fma_f32 v[14:15], v[14:15], v[214:215], v[162:163]
	v_pk_fma_f32 v[16:17], v[16:17], v[212:213], v[164:165]
	v_pk_fma_f32 v[18:19], v[18:19], v[214:215], v[166:167]
	v_pk_fma_f32 v[20:21], v[20:21], v[212:213], v[168:169]
	v_pk_fma_f32 v[22:23], v[22:23], v[214:215], v[170:171]
	v_pk_fma_f32 v[24:25], v[24:25], v[212:213], v[172:173]
	v_pk_fma_f32 v[26:27], v[26:27], v[214:215], v[174:175]
	v_pk_fma_f32 v[28:29], v[28:29], v[212:213], v[176:177]
	v_pk_fma_f32 v[30:31], v[30:31], v[214:215], v[178:179]
	s_cmp_eq_u32 s46, 7
	s_cbranch_scc1 .Lpf_done
	s_waitcnt vmcnt(33)
	s_min_i32 s48, 9, s47
	s_add_i32 s42, s39, s48
	s_ashr_i32 s43, s42, 31
	s_lshl_b64 s[44:45], s[42:43], 16
	s_add_u32 s44, s55, s44
	s_addc_u32 s45, s56, s45
	v_lshl_add_u64 v[132:133], v[40:41], 2, s[44:45]
	s_lshl_b32 s40, s48, 7
	s_add_i32 s40, s40, s33
	s_ashr_i32 s41, s40, 31
	v_lshl_add_u64 v[32:33], s[40:41], 2, v[62:63]
	global_load_dwordx4 v[212:215], v[32:33], off
	global_load_dword v148, v[132:133], off
	global_load_dword v149, v[132:133], off offset:512
	global_load_dword v150, v[132:133], off offset:1024
	global_load_dword v151, v[132:133], off offset:1536
	global_load_dword v152, v[132:133], off offset:64
	global_load_dword v153, v[132:133], off offset:576
	global_load_dword v154, v[132:133], off offset:1088
	global_load_dword v155, v[132:133], off offset:1600
	global_load_dword v156, v[132:133], off offset:128
	global_load_dword v157, v[132:133], off offset:640
	global_load_dword v158, v[132:133], off offset:1152
	global_load_dword v159, v[132:133], off offset:1664
	global_load_dword v160, v[132:133], off offset:192
	global_load_dword v161, v[132:133], off offset:704
	global_load_dword v162, v[132:133], off offset:1216
	global_load_dword v163, v[132:133], off offset:1728
	global_load_dword v164, v[132:133], off offset:256
	global_load_dword v165, v[132:133], off offset:768
	global_load_dword v166, v[132:133], off offset:1280
	global_load_dword v167, v[132:133], off offset:1792
	global_load_dword v168, v[132:133], off offset:320
	global_load_dword v169, v[132:133], off offset:832
	global_load_dword v170, v[132:133], off offset:1344
	global_load_dword v171, v[132:133], off offset:1856
	global_load_dword v172, v[132:133], off offset:384
	global_load_dword v173, v[132:133], off offset:896
	global_load_dword v174, v[132:133], off offset:1408
	global_load_dword v175, v[132:133], off offset:1920
	global_load_dword v176, v[132:133], off offset:448
	global_load_dword v177, v[132:133], off offset:960
	global_load_dword v178, v[132:133], off offset:1472
	global_load_dword v179, v[132:133], off offset:1984
	v_pk_fma_f32 v[0:1], v[0:1], v[216:217], v[180:181]
	v_pk_fma_f32 v[2:3], v[2:3], v[218:219], v[182:183]
	v_pk_fma_f32 v[4:5], v[4:5], v[216:217], v[184:185]
	v_pk_fma_f32 v[6:7], v[6:7], v[218:219], v[186:187]
	v_pk_fma_f32 v[8:9], v[8:9], v[216:217], v[188:189]
	v_pk_fma_f32 v[10:11], v[10:11], v[218:219], v[190:191]
	v_pk_fma_f32 v[12:13], v[12:13], v[216:217], v[192:193]
	v_pk_fma_f32 v[14:15], v[14:15], v[218:219], v[194:195]
	v_pk_fma_f32 v[16:17], v[16:17], v[216:217], v[196:197]
	v_pk_fma_f32 v[18:19], v[18:19], v[218:219], v[198:199]
	v_pk_fma_f32 v[20:21], v[20:21], v[216:217], v[200:201]
	v_pk_fma_f32 v[22:23], v[22:23], v[218:219], v[202:203]
	v_pk_fma_f32 v[24:25], v[24:25], v[216:217], v[204:205]
	v_pk_fma_f32 v[26:27], v[26:27], v[218:219], v[206:207]
	v_pk_fma_f32 v[28:29], v[28:29], v[216:217], v[208:209]
	v_pk_fma_f32 v[30:31], v[30:31], v[218:219], v[210:211]
	s_cmp_eq_u32 s46, 8
	s_cbranch_scc1 .Lpf_done
; __device__ __forceinline__ void hg2_unit(KP p, int u, unsigned char* shm, int tid) {
;     ...
;     for (int q = 0; q < sc; ++q) {
;       const float* SL = (const float*)(p->ws + WS_SLOC) + (size_t)(hd * 16 + q) * 16384; const float* DL = (const float*)(p->ws + WS_DLOC) + (hd * 16 + q) * 128;
; #pragma unroll
;       for (int j = 0; j < 4; ++j) { const float dc = DL[16 * wv + fq * 4 + j];
; #pragma unroll
;         for (int nt = 0; nt < 8; ++nt) Sacc[nt][j] = dc * Sacc[nt][j] + SL[(16 * wv + fq * 4 + j) * 128 + nt * 16 + fr]; }
;     }
	s_waitcnt vmcnt(33)
	s_min_i32 s48, 10, s47
	s_add_i32 s42, s39, s48
	s_ashr_i32 s43, s42, 31
	s_lshl_b64 s[44:45], s[42:43], 16
	s_add_u32 s44, s55, s44
	s_addc_u32 s45, s56, s45
	v_lshl_add_u64 v[134:135], v[40:41], 2, s[44:45]
	s_lshl_b32 s40, s48, 7
	s_add_i32 s40, s40, s33
	s_ashr_i32 s41, s40, 31
	v_lshl_add_u64 v[32:33], s[40:41], 2, v[62:63]
	global_load_dwordx4 v[216:219], v[32:33], off
	global_load_dword v180, v[134:135], off
	global_load_dword v181, v[134:135], off offset:512
	global_load_dword v182, v[134:135], off offset:1024
	global_load_dword v183, v[134:135], off offset:1536
	global_load_dword v184, v[134:135], off offset:64
	global_load_dword v185, v[134:135], off offset:576
	global_load_dword v186, v[134:135], off offset:1088
	global_load_dword v187, v[134:135], off offset:1600
	global_load_dword v188, v[134:135], off offset:128
	global_load_dword v189, v[134:135], off offset:640
	global_load_dword v190, v[134:135], off offset:1152
	global_load_dword v191, v[134:135], off offset:1664
	global_load_dword v192, v[134:135], off offset:192
	global_load_dword v193, v[134:135], off offset:704
	global_load_dword v194, v[134:135], off offset:1216
	global_load_dword v195, v[134:135], off offset:1728
	global_load_dword v196, v[134:135], off offset:256
	global_load_dword v197, v[134:135], off offset:768
	global_load_dword v198, v[134:135], off offset:1280
	global_load_dword v199, v[134:135], off offset:1792
	global_load_dword v200, v[134:135], off offset:320
	global_load_dword v201, v[134:135], off offset:832
	global_load_dword v202, v[134:135], off offset:1344
	global_load_dword v203, v[134:135], off offset:1856
	global_load_dword v204, v[134:135], off offset:384
	global_load_dword v205, v[134:135], off offset:896
	global_load_dword v206, v[134:135], off offset:1408
	global_load_dword v207, v[134:135], off offset:1920
	global_load_dword v208, v[134:135], off offset:448
	global_load_dword v209, v[134:135], off offset:960
	global_load_dword v210, v[134:135], off offset:1472
	global_load_dword v211, v[134:135], off offset:1984
	v_pk_fma_f32 v[0:1], v[0:1], v[128:129], v[68:69]
	v_pk_fma_f32 v[2:3], v[2:3], v[130:131], v[70:71]
	v_pk_fma_f32 v[4:5], v[4:5], v[128:129], v[72:73]
	v_pk_fma_f32 v[6:7], v[6:7], v[130:131], v[74:75]
	v_pk_fma_f32 v[8:9], v[8:9], v[128:129], v[76:77]
	v_pk_fma_f32 v[10:11], v[10:11], v[130:131], v[78:79]
	v_pk_fma_f32 v[12:13], v[12:13], v[128:129], v[80:81]
	v_pk_fma_f32 v[14:15], v[14:15], v[130:131], v[82:83]
	v_pk_fma_f32 v[16:17], v[16:17], v[128:129], v[112:113]
	v_pk_fma_f32 v[18:19], v[18:19], v[130:131], v[114:115]
	v_pk_fma_f32 v[20:21], v[20:21], v[128:129], v[116:117]
	v_pk_fma_f32 v[22:23], v[22:23], v[130:131], v[118:119]
	v_pk_fma_f32 v[24:25], v[24:25], v[128:129], v[120:121]
	v_pk_fma_f32 v[26:27], v[26:27], v[130:131], v[122:123]
	v_pk_fma_f32 v[28:29], v[28:29], v[128:129], v[124:125]
	v_pk_fma_f32 v[30:31], v[30:31], v[130:131], v[126:127]
	s_cmp_eq_u32 s46, 9
	s_cbranch_scc1 .Lpf_done
	s_waitcnt vmcnt(33)
	s_min_i32 s48, 11, s47
	s_add_i32 s42, s39, s48
	s_ashr_i32 s43, s42, 31
	s_lshl_b64 s[44:45], s[42:43], 16
	s_add_u32 s44, s55, s44
	s_addc_u32 s45, s56, s45
	v_lshl_add_u64 v[136:137], v[40:41], 2, s[44:45]
	s_lshl_b32 s40, s48, 7
	s_add_i32 s40, s40, s33
	s_ashr_i32 s41, s40, 31
	v_lshl_add_u64 v[32:33], s[40:41], 2, v[62:63]
	global_load_dwordx4 v[128:131], v[32:33], off
	global_load_dword v68, v[136:137], off
	global_load_dword v69, v[136:137], off offset:512
	global_load_dword v70, v[136:137], off offset:1024
	global_load_dword v71, v[136:137], off offset:1536
	global_load_dword v72, v[136:137], off offset:64
	global_load_dword v73, v[136:137], off offset:576
	global_load_dword v74, v[136:137], off offset:1088
	global_load_dword v75, v[136:137], off offset:1600
	global_load_dword v76, v[136:137], off offset:128
	global_load_dword v77, v[136:137], off offset:640
	global_load_dword v78, v[136:137], off offset:1152
	global_load_dword v79, v[136:137], off offset:1664
	global_load_dword v80, v[136:137], off offset:192
	global_load_dword v81, v[136:137], off offset:704
	global_load_dword v82, v[136:137], off offset:1216
	global_load_dword v83, v[136:137], off offset:1728
	global_load_dword v112, v[136:137], off offset:256
	global_load_dword v113, v[136:137], off offset:768
	global_load_dword v114, v[136:137], off offset:1280
	global_load_dword v115, v[136:137], off offset:1792
	global_load_dword v116, v[136:137], off offset:320
	global_load_dword v117, v[136:137], off offset:832
	global_load_dword v118, v[136:137], off offset:1344
	global_load_dword v119, v[136:137], off offset:1856
	global_load_dword v120, v[136:137], off offset:384
	global_load_dword v121, v[136:137], off offset:896
	global_load_dword v122, v[136:137], off offset:1408
	global_load_dword v123, v[136:137], off offset:1920
	global_load_dword v124, v[136:137], off offset:448
	global_load_dword v125, v[136:137], off offset:960
	global_load_dword v126, v[136:137], off offset:1472
	global_load_dword v127, v[136:137], off offset:1984
	v_pk_fma_f32 v[0:1], v[0:1], v[212:213], v[148:149]
	v_pk_fma_f32 v[2:3], v[2:3], v[214:215], v[150:151]
	v_pk_fma_f32 v[4:5], v[4:5], v[212:213], v[152:153]
	v_pk_fma_f32 v[6:7], v[6:7], v[214:215], v[154:155]
	v_pk_fma_f32 v[8:9], v[8:9], v[212:213], v[156:157]
	v_pk_fma_f32 v[10:11], v[10:11], v[214:215], v[158:159]
	v_pk_fma_f32 v[12:13], v[12:13], v[212:213], v[160:161]
	v_pk_fma_f32 v[14:15], v[14:15], v[214:215], v[162:163]
	v_pk_fma_f32 v[16:17], v[16:17], v[212:213], v[164:165]
	v_pk_fma_f32 v[18:19], v[18:19], v[214:215], v[166:167]
	v_pk_fma_f32 v[20:21], v[20:21], v[212:213], v[168:169]
	v_pk_fma_f32 v[22:23], v[22:23], v[214:215], v[170:171]
	v_pk_fma_f32 v[24:25], v[24:25], v[212:213], v[172:173]
	v_pk_fma_f32 v[26:27], v[26:27], v[214:215], v[174:175]
	v_pk_fma_f32 v[28:29], v[28:29], v[212:213], v[176:177]
	v_pk_fma_f32 v[30:31], v[30:31], v[214:215], v[178:179]
	s_cmp_eq_u32 s46, 10
	s_cbranch_scc1 .Lpf_done
; __device__ __forceinline__ void hg2_unit(KP p, int u, unsigned char* shm, int tid) {
;     ...
;     for (int q = 0; q < sc; ++q) {
;       const float* SL = (const float*)(p->ws + WS_SLOC) + (size_t)(hd * 16 + q) * 16384; const float* DL = (const float*)(p->ws + WS_DLOC) + (hd * 16 + q) * 128;
; #pragma unroll
;       for (int j = 0; j < 4; ++j) { const float dc = DL[16 * wv + fq * 4 + j];
; #pragma unroll
;         for (int nt = 0; nt < 8; ++nt) Sacc[nt][j] = dc * Sacc[nt][j] + SL[(16 * wv + fq * 4 + j) * 128 + nt * 16 + fr]; }
;     }
	s_waitcnt vmcnt(33)
	s_min_i32 s48, 12, s47
	s_add_i32 s42, s39, s48
	s_ashr_i32 s43, s42, 31
	s_lshl_b64 s[44:45], s[42:43], 16
	s_add_u32 s44, s55, s44
	s_addc_u32 s45, s56, s45
	v_lshl_add_u64 v[132:133], v[40:41], 2, s[44:45]
	s_lshl_b32 s40, s48, 7
	s_add_i32 s40, s40, s33
	s_ashr_i32 s41, s40, 31
	v_lshl_add_u64 v[32:33], s[40:41], 2, v[62:63]
	global_load_dwordx4 v[212:215], v[32:33], off
	global_load_dword v148, v[132:133], off
	global_load_dword v149, v[132:133], off offset:512
	global_load_dword v150, v[132:133], off offset:1024
	global_load_dword v151, v[132:133], off offset:1536
	global_load_dword v152, v[132:133], off offset:64
	global_load_dword v153, v[132:133], off offset:576
	global_load_dword v154, v[132:133], off offset:1088
	global_load_dword v155, v[132:133], off offset:1600
	global_load_dword v156, v[132:133], off offset:128
	global_load_dword v157, v[132:133], off offset:640
	global_load_dword v158, v[132:133], off offset:1152
	global_load_dword v159, v[132:133], off offset:1664
	global_load_dword v160, v[132:133], off offset:192
	global_load_dword v161, v[132:133], off offset:704
	global_load_dword v162, v[132:133], off offset:1216
	global_load_dword v163, v[132:133], off offset:1728
	global_load_dword v164, v[132:133], off offset:256
	global_load_dword v165, v[132:133], off offset:768
	global_load_dword v166, v[132:133], off offset:1280
	global_load_dword v167, v[132:133], off offset:1792
	global_load_dword v168, v[132:133], off offset:320
	global_load_dword v169, v[132:133], off offset:832
	global_load_dword v170, v[132:133], off offset:1344
	global_load_dword v171, v[132:133], off offset:1856
	global_load_dword v172, v[132:133], off offset:384
	global_load_dword v173, v[132:133], off offset:896
	global_load_dword v174, v[132:133], off offset:1408
	global_load_dword v175, v[132:133], off offset:1920
	global_load_dword v176, v[132:133], off offset:448
	global_load_dword v177, v[132:133], off offset:960
	global_load_dword v178, v[132:133], off offset:1472
	global_load_dword v179, v[132:133], off offset:1984
	v_pk_fma_f32 v[0:1], v[0:1], v[216:217], v[180:181]
	v_pk_fma_f32 v[2:3], v[2:3], v[218:219], v[182:183]
	v_pk_fma_f32 v[4:5], v[4:5], v[216:217], v[184:185]
	v_pk_fma_f32 v[6:7], v[6:7], v[218:219], v[186:187]
	v_pk_fma_f32 v[8:9], v[8:9], v[216:217], v[188:189]
	v_pk_fma_f32 v[10:11], v[10:11], v[218:219], v[190:191]
	v_pk_fma_f32 v[12:13], v[12:13], v[216:217], v[192:193]
	v_pk_fma_f32 v[14:15], v[14:15], v[218:219], v[194:195]
	v_pk_fma_f32 v[16:17], v[16:17], v[216:217], v[196:197]
	v_pk_fma_f32 v[18:19], v[18:19], v[218:219], v[198:199]
	v_pk_fma_f32 v[20:21], v[20:21], v[216:217], v[200:201]
	v_pk_fma_f32 v[22:23], v[22:23], v[218:219], v[202:203]
	v_pk_fma_f32 v[24:25], v[24:25], v[216:217], v[204:205]
	v_pk_fma_f32 v[26:27], v[26:27], v[218:219], v[206:207]
	v_pk_fma_f32 v[28:29], v[28:29], v[216:217], v[208:209]
	v_pk_fma_f32 v[30:31], v[30:31], v[218:219], v[210:211]
	s_cmp_eq_u32 s46, 11
	s_cbranch_scc1 .Lpf_done
	s_waitcnt vmcnt(33)
	s_min_i32 s48, 13, s47
	s_add_i32 s42, s39, s48
	s_ashr_i32 s43, s42, 31
	s_lshl_b64 s[44:45], s[42:43], 16
	s_add_u32 s44, s55, s44
	s_addc_u32 s45, s56, s45
	v_lshl_add_u64 v[134:135], v[40:41], 2, s[44:45]
	s_lshl_b32 s40, s48, 7
	s_add_i32 s40, s40, s33
	s_ashr_i32 s41, s40, 31
	v_lshl_add_u64 v[32:33], s[40:41], 2, v[62:63]
	global_load_dwordx4 v[216:219], v[32:33], off
	global_load_dword v180, v[134:135], off
	global_load_dword v181, v[134:135], off offset:512
	global_load_dword v182, v[134:135], off offset:1024
	global_load_dword v183, v[134:135], off offset:1536
	global_load_dword v184, v[134:135], off offset:64
	global_load_dword v185, v[134:135], off offset:576
	global_load_dword v186, v[134:135], off offset:1088
	global_load_dword v187, v[134:135], off offset:1600
	global_load_dword v188, v[134:135], off offset:128
	global_load_dword v189, v[134:135], off offset:640
	global_load_dword v190, v[134:135], off offset:1152
	global_load_dword v191, v[134:135], off offset:1664
	global_load_dword v192, v[134:135], off offset:192
	global_load_dword v193, v[134:135], off offset:704
	global_load_dword v194, v[134:135], off offset:1216
	global_load_dword v195, v[134:135], off offset:1728
	global_load_dword v196, v[134:135], off offset:256
	global_load_dword v197, v[134:135], off offset:768
	global_load_dword v198, v[134:135], off offset:1280
	global_load_dword v199, v[134:135], off offset:1792
	global_load_dword v200, v[134:135], off offset:320
	global_load_dword v201, v[134:135], off offset:832
	global_load_dword v202, v[134:135], off offset:1344
	global_load_dword v203, v[134:135], off offset:1856
	global_load_dword v204, v[134:135], off offset:384
	global_load_dword v205, v[134:135], off offset:896
	global_load_dword v206, v[134:135], off offset:1408
	global_load_dword v207, v[134:135], off offset:1920
	global_load_dword v208, v[134:135], off offset:448
	global_load_dword v209, v[134:135], off offset:960
	global_load_dword v210, v[134:135], off offset:1472
	global_load_dword v211, v[134:135], off offset:1984
	v_pk_fma_f32 v[0:1], v[0:1], v[128:129], v[68:69]
	v_pk_fma_f32 v[2:3], v[2:3], v[130:131], v[70:71]
	v_pk_fma_f32 v[4:5], v[4:5], v[128:129], v[72:73]
	v_pk_fma_f32 v[6:7], v[6:7], v[130:131], v[74:75]
	v_pk_fma_f32 v[8:9], v[8:9], v[128:129], v[76:77]
	v_pk_fma_f32 v[10:11], v[10:11], v[130:131], v[78:79]
	v_pk_fma_f32 v[12:13], v[12:13], v[128:129], v[80:81]
	v_pk_fma_f32 v[14:15], v[14:15], v[130:131], v[82:83]
	v_pk_fma_f32 v[16:17], v[16:17], v[128:129], v[112:113]
	v_pk_fma_f32 v[18:19], v[18:19], v[130:131], v[114:115]
	v_pk_fma_f32 v[20:21], v[20:21], v[128:129], v[116:117]
	v_pk_fma_f32 v[22:23], v[22:23], v[130:131], v[118:119]
	v_pk_fma_f32 v[24:25], v[24:25], v[128:129], v[120:121]
	v_pk_fma_f32 v[26:27], v[26:27], v[130:131], v[122:123]
	v_pk_fma_f32 v[28:29], v[28:29], v[128:129], v[124:125]
	v_pk_fma_f32 v[30:31], v[30:31], v[130:131], v[126:127]
	s_cmp_eq_u32 s46, 12
	s_cbranch_scc1 .Lpf_done
; __device__ __forceinline__ void hg2_unit(KP p, int u, unsigned char* shm, int tid) {
;     ...
;     for (int q = 0; q < sc; ++q) {
;       const float* SL = (const float*)(p->ws + WS_SLOC) + (size_t)(hd * 16 + q) * 16384; const float* DL = (const float*)(p->ws + WS_DLOC) + (hd * 16 + q) * 128;
; #pragma unroll
;       for (int j = 0; j < 4; ++j) { const float dc = DL[16 * wv + fq * 4 + j];
; #pragma unroll
;         for (int nt = 0; nt < 8; ++nt) Sacc[nt][j] = dc * Sacc[nt][j] + SL[(16 * wv + fq * 4 + j) * 128 + nt * 16 + fr]; }
;     }
	s_waitcnt vmcnt(33)
	s_min_i32 s48, 14, s47
	s_add_i32 s42, s39, s48
	s_ashr_i32 s43, s42, 31
	s_lshl_b64 s[44:45], s[42:43], 16
	s_add_u32 s44, s55, s44
	s_addc_u32 s45, s56, s45
	v_lshl_add_u64 v[136:137], v[40:41], 2, s[44:45]
	s_lshl_b32 s40, s48, 7
	s_add_i32 s40, s40, s33
	s_ashr_i32 s41, s40, 31
	v_lshl_add_u64 v[32:33], s[40:41], 2, v[62:63]
	global_load_dwordx4 v[128:131], v[32:33], off
	global_load_dword v68, v[136:137], off
	global_load_dword v69, v[136:137], off offset:512
	global_load_dword v70, v[136:137], off offset:1024
	global_load_dword v71, v[136:137], off offset:1536
	global_load_dword v72, v[136:137], off offset:64
	global_load_dword v73, v[136:137], off offset:576
	global_load_dword v74, v[136:137], off offset:1088
	global_load_dword v75, v[136:137], off offset:1600
	global_load_dword v76, v[136:137], off offset:128
	global_load_dword v77, v[136:137], off offset:640
	global_load_dword v78, v[136:137], off offset:1152
	global_load_dword v79, v[136:137], off offset:1664
	global_load_dword v80, v[136:137], off offset:192
	global_load_dword v81, v[136:137], off offset:704
	global_load_dword v82, v[136:137], off offset:1216
	global_load_dword v83, v[136:137], off offset:1728
	global_load_dword v112, v[136:137], off offset:256
	global_load_dword v113, v[136:137], off offset:768
	global_load_dword v114, v[136:137], off offset:1280
	global_load_dword v115, v[136:137], off offset:1792
	global_load_dword v116, v[136:137], off offset:320
	global_load_dword v117, v[136:137], off offset:832
	global_load_dword v118, v[136:137], off offset:1344
	global_load_dword v119, v[136:137], off offset:1856
	global_load_dword v120, v[136:137], off offset:384
	global_load_dword v121, v[136:137], off offset:896
	global_load_dword v122, v[136:137], off offset:1408
	global_load_dword v123, v[136:137], off offset:1920
	global_load_dword v124, v[136:137], off offset:448
	global_load_dword v125, v[136:137], off offset:960
	global_load_dword v126, v[136:137], off offset:1472
	global_load_dword v127, v[136:137], off offset:1984
	v_pk_fma_f32 v[0:1], v[0:1], v[212:213], v[148:149]
	v_pk_fma_f32 v[2:3], v[2:3], v[214:215], v[150:151]
	v_pk_fma_f32 v[4:5], v[4:5], v[212:213], v[152:153]
	v_pk_fma_f32 v[6:7], v[6:7], v[214:215], v[154:155]
	v_pk_fma_f32 v[8:9], v[8:9], v[212:213], v[156:157]
	v_pk_fma_f32 v[10:11], v[10:11], v[214:215], v[158:159]
	v_pk_fma_f32 v[12:13], v[12:13], v[212:213], v[160:161]
	v_pk_fma_f32 v[14:15], v[14:15], v[214:215], v[162:163]
	v_pk_fma_f32 v[16:17], v[16:17], v[212:213], v[164:165]
	v_pk_fma_f32 v[18:19], v[18:19], v[214:215], v[166:167]
	v_pk_fma_f32 v[20:21], v[20:21], v[212:213], v[168:169]
	v_pk_fma_f32 v[22:23], v[22:23], v[214:215], v[170:171]
	v_pk_fma_f32 v[24:25], v[24:25], v[212:213], v[172:173]
	v_pk_fma_f32 v[26:27], v[26:27], v[214:215], v[174:175]
	v_pk_fma_f32 v[28:29], v[28:29], v[212:213], v[176:177]
	v_pk_fma_f32 v[30:31], v[30:31], v[214:215], v[178:179]
	s_cmp_eq_u32 s46, 13
	s_cbranch_scc1 .Lpf_done
	s_waitcnt vmcnt(33)
	s_min_i32 s48, 15, s47
	s_add_i32 s42, s39, s48
	s_ashr_i32 s43, s42, 31
	s_lshl_b64 s[44:45], s[42:43], 16
	s_add_u32 s44, s55, s44
	s_addc_u32 s45, s56, s45
	v_lshl_add_u64 v[132:133], v[40:41], 2, s[44:45]
	s_lshl_b32 s40, s48, 7
	s_add_i32 s40, s40, s33
	s_ashr_i32 s41, s40, 31
	v_lshl_add_u64 v[32:33], s[40:41], 2, v[62:63]
	global_load_dwordx4 v[212:215], v[32:33], off
	global_load_dword v148, v[132:133], off
	global_load_dword v149, v[132:133], off offset:512
	global_load_dword v150, v[132:133], off offset:1024
	global_load_dword v151, v[132:133], off offset:1536
	global_load_dword v152, v[132:133], off offset:64
	global_load_dword v153, v[132:133], off offset:576
	global_load_dword v154, v[132:133], off offset:1088
	global_load_dword v155, v[132:133], off offset:1600
	global_load_dword v156, v[132:133], off offset:128
	global_load_dword v157, v[132:133], off offset:640
	global_load_dword v158, v[132:133], off offset:1152
	global_load_dword v159, v[132:133], off offset:1664
	global_load_dword v160, v[132:133], off offset:192
	global_load_dword v161, v[132:133], off offset:704
	global_load_dword v162, v[132:133], off offset:1216
	global_load_dword v163, v[132:133], off offset:1728
	global_load_dword v164, v[132:133], off offset:256
	global_load_dword v165, v[132:133], off offset:768
	global_load_dword v166, v[132:133], off offset:1280
	global_load_dword v167, v[132:133], off offset:1792
	global_load_dword v168, v[132:133], off offset:320
	global_load_dword v169, v[132:133], off offset:832
	global_load_dword v170, v[132:133], off offset:1344
	global_load_dword v171, v[132:133], off offset:1856
	global_load_dword v172, v[132:133], off offset:384
	global_load_dword v173, v[132:133], off offset:896
	global_load_dword v174, v[132:133], off offset:1408
	global_load_dword v175, v[132:133], off offset:1920
	global_load_dword v176, v[132:133], off offset:448
	global_load_dword v177, v[132:133], off offset:960
	global_load_dword v178, v[132:133], off offset:1472
	global_load_dword v179, v[132:133], off offset:1984
	v_pk_fma_f32 v[0:1], v[0:1], v[216:217], v[180:181]
	v_pk_fma_f32 v[2:3], v[2:3], v[218:219], v[182:183]
	v_pk_fma_f32 v[4:5], v[4:5], v[216:217], v[184:185]
	v_pk_fma_f32 v[6:7], v[6:7], v[218:219], v[186:187]
	v_pk_fma_f32 v[8:9], v[8:9], v[216:217], v[188:189]
	v_pk_fma_f32 v[10:11], v[10:11], v[218:219], v[190:191]
	v_pk_fma_f32 v[12:13], v[12:13], v[216:217], v[192:193]
	v_pk_fma_f32 v[14:15], v[14:15], v[218:219], v[194:195]
	v_pk_fma_f32 v[16:17], v[16:17], v[216:217], v[196:197]
	v_pk_fma_f32 v[18:19], v[18:19], v[218:219], v[198:199]
	v_pk_fma_f32 v[20:21], v[20:21], v[216:217], v[200:201]
	v_pk_fma_f32 v[22:23], v[22:23], v[218:219], v[202:203]
	v_pk_fma_f32 v[24:25], v[24:25], v[216:217], v[204:205]
	v_pk_fma_f32 v[26:27], v[26:27], v[218:219], v[206:207]
	v_pk_fma_f32 v[28:29], v[28:29], v[216:217], v[208:209]
	v_pk_fma_f32 v[30:31], v[30:31], v[218:219], v[210:211]
	s_cmp_eq_u32 s46, 14
	s_cbranch_scc1 .Lpf_done
; __device__ __forceinline__ unsigned cvt_pk_bf16(float lo, float hi) { unsigned r; asm volatile("v_cvt_pk_bf16_f32 %0, %1, %2" : "=v"(r) : "v"(lo), "v"(hi)); return r; }
; __device__ __forceinline__ void hg_write_st(const f32x4 (&Sacc)[8], unsigned char* shm, int wv, int fr, int fq) {
;   bf16_t* ST = (bf16_t*)(shm + HG_ST);
; #pragma unroll
;   for (int nt = 0; nt < 8; ++nt) {
;     u32x2 w; w.x = cvt_pk_bf16(Sacc[nt][0], Sacc[nt][1]); w.y = cvt_pk_bf16(Sacc[nt][2], Sacc[nt][3]);
;     *(u32x2*)(ST + (nt * 16 + fr) * 136 + 16 * wv + fq * 4) = w;
;   }
; __device__ __forceinline__ void hg2_unit(KP p, int u, unsigned char* shm, int tid) {
;     ...
;     for (int q = 0; q < sc; ++q) {
;       const float* SL = (const float*)(p->ws + WS_SLOC) + (size_t)(hd * 16 + q) * 16384; const float* DL = (const float*)(p->ws + WS_DLOC) + (hd * 16 + q) * 128;
; #pragma unroll
;       for (int j = 0; j < 4; ++j) { const float dc = DL[16 * wv + fq * 4 + j];
; #pragma unroll
;         for (int nt = 0; nt < 8; ++nt) Sacc[nt][j] = dc * Sacc[nt][j] + SL[(16 * wv + fq * 4 + j) * 128 + nt * 16 + fr]; }
;     }
	s_waitcnt vmcnt(33)
	s_min_i32 s48, 16, s47
	s_add_i32 s42, s39, s48
	s_ashr_i32 s43, s42, 31
	s_lshl_b64 s[44:45], s[42:43], 16
	s_add_u32 s44, s55, s44
	s_addc_u32 s45, s56, s45
	v_lshl_add_u64 v[134:135], v[40:41], 2, s[44:45]
	s_lshl_b32 s40, s48, 7
	s_add_i32 s40, s40, s33
	s_ashr_i32 s41, s40, 31
	v_lshl_add_u64 v[32:33], s[40:41], 2, v[62:63]
	global_load_dwordx4 v[216:219], v[32:33], off
	global_load_dword v180, v[134:135], off
	global_load_dword v181, v[134:135], off offset:512
	global_load_dword v182, v[134:135], off offset:1024
	global_load_dword v183, v[134:135], off offset:1536
	global_load_dword v184, v[134:135], off offset:64
	global_load_dword v185, v[134:135], off offset:576
	global_load_dword v186, v[134:135], off offset:1088
	global_load_dword v187, v[134:135], off offset:1600
	global_load_dword v188, v[134:135], off offset:128
	global_load_dword v189, v[134:135], off offset:640
	global_load_dword v190, v[134:135], off offset:1152
	global_load_dword v191, v[134:135], off offset:1664
	global_load_dword v192, v[134:135], off offset:192
	global_load_dword v193, v[134:135], off offset:704
	global_load_dword v194, v[134:135], off offset:1216
	global_load_dword v195, v[134:135], off offset:1728
	global_load_dword v196, v[134:135], off offset:256
	global_load_dword v197, v[134:135], off offset:768
	global_load_dword v198, v[134:135], off offset:1280
	global_load_dword v199, v[134:135], off offset:1792
	global_load_dword v200, v[134:135], off offset:320
	global_load_dword v201, v[134:135], off offset:832
	global_load_dword v202, v[134:135], off offset:1344
	global_load_dword v203, v[134:135], off offset:1856
	global_load_dword v204, v[134:135], off offset:384
	global_load_dword v205, v[134:135], off offset:896
	global_load_dword v206, v[134:135], off offset:1408
	global_load_dword v207, v[134:135], off offset:1920
	global_load_dword v208, v[134:135], off offset:448
	global_load_dword v209, v[134:135], off offset:960
	global_load_dword v210, v[134:135], off offset:1472
	global_load_dword v211, v[134:135], off offset:1984
	v_pk_fma_f32 v[0:1], v[0:1], v[128:129], v[68:69]
	v_pk_fma_f32 v[2:3], v[2:3], v[130:131], v[70:71]
	v_pk_fma_f32 v[4:5], v[4:5], v[128:129], v[72:73]
	v_pk_fma_f32 v[6:7], v[6:7], v[130:131], v[74:75]
	v_pk_fma_f32 v[8:9], v[8:9], v[128:129], v[76:77]
	v_pk_fma_f32 v[10:11], v[10:11], v[130:131], v[78:79]
	v_pk_fma_f32 v[12:13], v[12:13], v[128:129], v[80:81]
	v_pk_fma_f32 v[14:15], v[14:15], v[130:131], v[82:83]
	v_pk_fma_f32 v[16:17], v[16:17], v[128:129], v[112:113]
	v_pk_fma_f32 v[18:19], v[18:19], v[130:131], v[114:115]
	v_pk_fma_f32 v[20:21], v[20:21], v[128:129], v[116:117]
	v_pk_fma_f32 v[22:23], v[22:23], v[130:131], v[118:119]
	v_pk_fma_f32 v[24:25], v[24:25], v[128:129], v[120:121]
	v_pk_fma_f32 v[26:27], v[26:27], v[130:131], v[122:123]
	v_pk_fma_f32 v[28:29], v[28:29], v[128:129], v[124:125]
	v_pk_fma_f32 v[30:31], v[30:31], v[130:131], v[126:127]
.Lpf_done:
	s_waitcnt vmcnt(0)
.LBB0_79:
	s_lshl_b32 s33, s37, 10
	s_ashr_i32 s37, s36, 31
	v_subrev_u32_e32 v70, s33, v97
	v_or_b32_e32 v71, s33, v89
	s_and_b32 s33, s38, 1
	s_lshl_b64 s[36:37], s[36:37], 1
	s_add_u32 s42, s26, s36
	s_addc_u32 s43, s51, s37
	s_lshl_b32 s38, s33, 11
	s_add_u32 s38, s42, s38
	s_waitcnt vmcnt(30)
	v_cvt_pk_bf16_f32 v32, v0, v1
	s_addc_u32 s39, s43, 0
	s_waitcnt vmcnt(28)
	v_cvt_pk_bf16_f32 v33, v2, v3
	ds_write_b64 v109, v[32:33]
	s_waitcnt vmcnt(26)
	v_cvt_pk_bf16_f32 v32, v4, v5
	s_add_u32 s44, s38, 0x1000
	s_waitcnt vmcnt(24)
	v_cvt_pk_bf16_f32 v33, v6, v7
	ds_write_b64 v109, v[32:33] offset:4352
	s_waitcnt vmcnt(22)
	v_cvt_pk_bf16_f32 v32, v8, v9
	s_addc_u32 s45, s39, 0
	s_waitcnt vmcnt(20)
	v_cvt_pk_bf16_f32 v33, v10, v11
	ds_write_b64 v109, v[32:33] offset:8704
	s_waitcnt vmcnt(18)
	v_cvt_pk_bf16_f32 v32, v12, v13
	s_lshl_b32 s38, s33, 25
	s_waitcnt vmcnt(16)
	v_cvt_pk_bf16_f32 v33, v14, v15
	ds_write_b64 v109, v[32:33] offset:13056
	s_waitcnt vmcnt(14)
	v_cvt_pk_bf16_f32 v32, v16, v17
	s_add_u32 s38, s57, s38
	s_waitcnt vmcnt(12)
	v_cvt_pk_bf16_f32 v33, v18, v19
	ds_write_b64 v109, v[32:33] offset:17408
	s_waitcnt vmcnt(10)
	v_cvt_pk_bf16_f32 v32, v20, v21
	s_addc_u32 s39, s59, 0
	s_waitcnt vmcnt(8)
	v_cvt_pk_bf16_f32 v33, v22, v23
	ds_write_b64 v109, v[32:33] offset:21760
	s_waitcnt vmcnt(6)
	v_cvt_pk_bf16_f32 v32, v24, v25
	s_add_u32 s38, s38, s36
	s_waitcnt vmcnt(4)
	v_cvt_pk_bf16_f32 v33, v26, v27
	ds_write_b64 v109, v[32:33] offset:26112
	s_waitcnt vmcnt(2)
	v_cvt_pk_bf16_f32 v32, v28, v29
	s_addc_u32 s39, s39, s37
	s_lshl_b32 s68, s46, 4
	s_waitcnt vmcnt(0)
	v_cvt_pk_bf16_f32 v33, v30, v31
	ds_write_b64 v109, v[32:33] offset:30464
	v_lshl_add_u32 v32, s46, 10, v39
	s_cmp_eq_u32 s33, 0
	s_cselect_b64 s[36:37], -1, 0
	v_sub_u32_e32 v33, 0x3fff, v32
	v_cndmask_b32_e64 v32, v33, v32, s[36:37]
	s_movk_i32 s33, 0x1400
	v_mad_i64_i32 v[32:33], s[40:41], v32, s33, 0
	v_or_b32_e32 v32, v32, v38
	v_lshlrev_b64 v[32:33], 1, v[32:33]
	v_lshl_add_u64 v[34:35], s[44:45], 0, v[32:33]
	s_waitcnt lgkmcnt(0)
	s_barrier
; template <bool WITHQ>
; __device__ __forceinline__ void hg_load(const HgSrc& s, int dir, int n, int tid, HgRaw& r) {
;   const int k = tid & 127, sg = tid >> 7;
;   const int sp0 = n * 64 + sg * 16; const int tb = dir ? (s.len - 1 - sp0) : sp0; const int step = dir ? -s.ld : s.ld;
;   const size_t ob = (size_t)tb * s.ld + k;
;   const bf16_t* pf = s.f + ob; const bf16_t* pv = s.v + ob; const bf16_t* pq = s.q + ob;
; #pragma unroll
;   for (int j = 0; j < 16; j += 2) {
;     const int r0 = j * step, r1 = (j + 1) * step;
;     r.fv[j] = (unsigned)pf[r0] | ((unsigned)pv[r0] << 16); r.fv[j + 1] = (unsigned)pf[r1] | ((unsigned)pv[r1] << 16);
;     if (WITHQ) r.q2[j >> 1] = (unsigned)pq[r0] | ((unsigned)pq[r1] << 16);
;   }
; }
	v_lshl_add_u64 v[32:33], s[42:43], 0, v[32:33]
	global_load_ushort v36, v[34:35], off
	global_load_ushort v37, v[32:33], off offset:2048
	s_and_b64 s[40:41], s[36:37], exec
	s_movk_i32 s33, 0xec00
	s_cselect_b32 s41, 0, -1
	s_cselect_b32 s40, 0x1400, s33
	s_lshl_b64 s[46:47], s[40:41], 1
	v_lshl_add_u64 v[34:35], v[34:35], 0, s[46:47]
	v_lshl_add_u64 v[68:69], v[32:33], 0, s[46:47]
	s_sub_u32 s48, 0, s46
	s_subb_u32 s49, 0, s47
	s_mov_b32 s67, 1
	s_mov_b32 s69, 0
	v_sub_f32_e32 v79, 1.0, v111
	global_load_ushort v72, v[68:69], off offset:2048
	s_waitcnt vmcnt(1)
	v_lshl_or_b32 v36, v37, 16, v36
	global_load_ushort v37, v[34:35], off
	s_nop 0
	global_load_ushort v32, v[32:33], off
	s_nop 0
	global_load_ushort v33, v[68:69], off
	s_waitcnt vmcnt(2)
	v_lshl_or_b32 v37, v72, 16, v37
	s_waitcnt vmcnt(0)
	v_lshl_or_b32 v115, v33, 16, v32
	v_lshl_add_u64 v[32:33], v[34:35], 0, s[46:47]
	v_lshl_add_u64 v[34:35], v[68:69], 0, s[46:47]
	global_load_ushort v72, v[32:33], off
	global_load_ushort v68, v[34:35], off offset:2048
	v_lshl_add_u64 v[32:33], v[32:33], 0, s[46:47]
	v_lshl_add_u64 v[34:35], v[34:35], 0, s[46:47]
	global_load_ushort v69, v[34:35], off offset:2048
	v_lshl_add_u64 v[34:35], v[34:35], 0, s[48:49]
	s_waitcnt vmcnt(1)
	v_lshl_or_b32 v72, v68, 16, v72
	global_load_ushort v68, v[32:33], off
	v_lshl_add_u64 v[32:33], v[32:33], 0, s[46:47]
	s_waitcnt vmcnt(0)
	v_lshl_or_b32 v73, v69, 16, v68
	global_load_ushort v68, v[34:35], off
	v_lshl_add_u64 v[34:35], v[34:35], 0, s[46:47]
	global_load_ushort v69, v[34:35], off
	v_lshl_add_u64 v[34:35], v[34:35], 0, s[46:47]
	s_waitcnt vmcnt(0)
	v_lshl_or_b32 v119, v69, 16, v68
	global_load_ushort v68, v[32:33], off
	global_load_ushort v69, v[34:35], off offset:2048
	v_lshl_add_u64 v[32:33], v[32:33], 0, s[46:47]
	v_lshl_add_u64 v[34:35], v[34:35], 0, s[46:47]
	s_waitcnt vmcnt(0)
	v_lshl_or_b32 v74, v69, 16, v68
	global_load_ushort v68, v[32:33], off
	global_load_ushort v69, v[34:35], off offset:2048
	v_lshl_add_u64 v[34:35], v[34:35], 0, s[48:49]
	v_lshl_add_u64 v[32:33], v[32:33], 0, s[46:47]
	s_waitcnt vmcnt(0)
	v_lshl_or_b32 v75, v69, 16, v68
	global_load_ushort v68, v[34:35], off
	v_lshl_add_u64 v[34:35], v[34:35], 0, s[46:47]
	global_load_ushort v69, v[34:35], off
	v_lshl_add_u64 v[34:35], v[34:35], 0, s[46:47]
	s_waitcnt vmcnt(0)
	v_lshl_or_b32 v121, v69, 16, v68
	global_load_ushort v68, v[32:33], off
	global_load_ushort v69, v[34:35], off offset:2048
	v_lshl_add_u64 v[32:33], v[32:33], 0, s[46:47]
	v_lshl_add_u64 v[34:35], v[34:35], 0, s[46:47]
	s_waitcnt vmcnt(0)
	v_lshl_or_b32 v76, v69, 16, v68
	global_load_ushort v68, v[32:33], off
	global_load_ushort v69, v[34:35], off offset:2048
	v_lshl_add_u64 v[34:35], v[34:35], 0, s[48:49]
	v_lshl_add_u64 v[32:33], v[32:33], 0, s[46:47]
	s_waitcnt vmcnt(0)
	v_lshl_or_b32 v77, v69, 16, v68
	global_load_ushort v68, v[34:35], off
	v_lshl_add_u64 v[34:35], v[34:35], 0, s[46:47]
	global_load_ushort v69, v[34:35], off
	v_lshl_add_u64 v[34:35], v[34:35], 0, s[46:47]
	s_waitcnt vmcnt(0)
	v_lshl_or_b32 v120, v69, 16, v68
	global_load_ushort v68, v[32:33], off
	global_load_ushort v69, v[34:35], off offset:2048
	v_lshl_add_u64 v[32:33], v[32:33], 0, s[46:47]
	v_lshl_add_u64 v[34:35], v[34:35], 0, s[46:47]
	s_waitcnt vmcnt(0)
	v_lshl_or_b32 v78, v69, 16, v68
	global_load_ushort v68, v[32:33], off
	global_load_ushort v69, v[34:35], off offset:2048
	v_lshl_add_u64 v[34:35], v[34:35], 0, s[48:49]
	v_lshl_add_u64 v[32:33], v[32:33], 0, s[46:47]
	s_waitcnt vmcnt(0)
	v_lshl_or_b32 v80, v69, 16, v68
	global_load_ushort v68, v[34:35], off
	v_lshl_add_u64 v[34:35], v[34:35], 0, s[46:47]
	global_load_ushort v69, v[34:35], off
	v_lshl_add_u64 v[34:35], v[34:35], 0, s[46:47]
	s_waitcnt vmcnt(0)
	v_lshl_or_b32 v118, v69, 16, v68
	global_load_ushort v68, v[32:33], off
	global_load_ushort v69, v[34:35], off offset:2048
	v_lshl_add_u64 v[32:33], v[32:33], 0, s[46:47]
	v_lshl_add_u64 v[34:35], v[34:35], 0, s[46:47]
	s_waitcnt vmcnt(0)
	v_lshl_or_b32 v81, v69, 16, v68
	global_load_ushort v68, v[32:33], off
	global_load_ushort v69, v[34:35], off offset:2048
	v_lshl_add_u64 v[34:35], v[34:35], 0, s[48:49]
	v_lshl_add_u64 v[32:33], v[32:33], 0, s[46:47]
	s_waitcnt vmcnt(0)
	v_lshl_or_b32 v82, v69, 16, v68
	global_load_ushort v68, v[34:35], off
	v_lshl_add_u64 v[34:35], v[34:35], 0, s[46:47]
	global_load_ushort v69, v[34:35], off
	v_lshl_add_u64 v[34:35], v[34:35], 0, s[46:47]
	s_waitcnt vmcnt(0)
	v_lshl_or_b32 v117, v69, 16, v68
	global_load_ushort v68, v[32:33], off
	global_load_ushort v69, v[34:35], off offset:2048
	v_lshl_add_u64 v[32:33], v[32:33], 0, s[46:47]
	v_lshl_add_u64 v[34:35], v[34:35], 0, s[46:47]
	s_waitcnt vmcnt(0)
	v_lshl_or_b32 v83, v69, 16, v68
	global_load_ushort v68, v[32:33], off
	global_load_ushort v69, v[34:35], off offset:2048
	v_lshl_add_u64 v[34:35], v[34:35], 0, s[48:49]
	v_lshl_add_u64 v[32:33], v[32:33], 0, s[46:47]
	s_waitcnt vmcnt(0)
	v_lshl_or_b32 v112, v69, 16, v68
	global_load_ushort v68, v[34:35], off
	v_lshl_add_u64 v[34:35], v[34:35], 0, s[46:47]
	global_load_ushort v69, v[34:35], off
	v_lshl_add_u64 v[34:35], v[34:35], 0, s[46:47]
	s_waitcnt vmcnt(0)
	v_lshl_or_b32 v116, v69, 16, v68
	global_load_ushort v68, v[32:33], off
	global_load_ushort v69, v[34:35], off offset:2048
	v_lshl_add_u64 v[32:33], v[32:33], 0, s[46:47]
	s_waitcnt vmcnt(0)
	v_lshl_or_b32 v113, v69, 16, v68
	global_load_ushort v68, v[32:33], off
	v_lshl_add_u64 v[32:33], v[34:35], 0, s[46:47]
	global_load_ushort v34, v[32:33], off offset:2048
	v_lshl_add_u64 v[32:33], v[32:33], 0, s[48:49]
	s_waitcnt vmcnt(0)
	v_lshl_or_b32 v114, v34, 16, v68
	global_load_ushort v34, v[32:33], off
	v_lshl_add_u64 v[32:33], v[32:33], 0, s[46:47]
	global_load_ushort v32, v[32:33], off
	v_lshl_add_u64 v[68:69], s[38:39], 0, v[138:139]
	s_waitcnt vmcnt(0)
	v_lshl_or_b32 v122, v32, 16, v34
	s_branch .LBB0_81
